# adaLN modulation GEMV loop: 8 steps per trip with their 32 weight loads issued up front (same fma order)
# baseline (speedup 1.0000x reference)
; DI void mod_phase(const P& p, float* sm) {
;     ...
;     for (int d = ds * 128; d < ds * 128 + 128; ++d) {
;       float wv = w[(size_t)d * 6144];
; #pragma unroll
;       for (int r = 0; r < 5; ++r) acc[r] += sl[r * 1024 + d] * wv;
;     }
.LBB0_55:
	v_lshl_add_u64 v[16:17], v[6:7], 0, s[6:7]
	v_add_co_u32_e64 v18, s[0:1], s3, v16
	global_load_dword v130, v[16:17], off
	s_nop 0
	v_addc_co_u32_e64 v19, s[0:1], 0, v17, s[0:1]
	v_add_co_u32_e64 v20, s[0:1], s8, v16
	s_add_u32 s6, s6, 0x18000
	s_nop 0
	v_addc_co_u32_e64 v21, s[0:1], 0, v17, s[0:1]
	v_add_co_u32_e64 v16, s[0:1], s9, v16
	s_addc_u32 s7, s7, 0
	s_nop 0
	v_addc_co_u32_e64 v17, s[0:1], 0, v17, s[0:1]
	global_load_dword v132, v[18:19], off
	global_load_dword v134, v[20:21], off
	global_load_dword v136, v[16:17], off
	v_lshl_add_u64 v[16:17], v[6:7], 0, s[6:7]
	v_add_co_u32_e64 v18, s[0:1], s3, v16
	global_load_dword v138, v[16:17], off
	s_nop 0
	v_addc_co_u32_e64 v19, s[0:1], 0, v17, s[0:1]
	v_add_co_u32_e64 v20, s[0:1], s8, v16
	s_add_u32 s6, s6, 0x18000
	s_nop 0
	v_addc_co_u32_e64 v21, s[0:1], 0, v17, s[0:1]
	v_add_co_u32_e64 v16, s[0:1], s9, v16
	s_addc_u32 s7, s7, 0
	s_nop 0
	v_addc_co_u32_e64 v17, s[0:1], 0, v17, s[0:1]
	global_load_dword v140, v[18:19], off
	global_load_dword v142, v[20:21], off
	global_load_dword v144, v[16:17], off
	v_lshl_add_u64 v[16:17], v[6:7], 0, s[6:7]
	v_add_co_u32_e64 v18, s[0:1], s3, v16
	global_load_dword v146, v[16:17], off
	s_nop 0
	v_addc_co_u32_e64 v19, s[0:1], 0, v17, s[0:1]
	v_add_co_u32_e64 v20, s[0:1], s8, v16
	s_add_u32 s6, s6, 0x18000
	s_nop 0
	v_addc_co_u32_e64 v21, s[0:1], 0, v17, s[0:1]
	v_add_co_u32_e64 v16, s[0:1], s9, v16
	s_addc_u32 s7, s7, 0
	s_nop 0
	v_addc_co_u32_e64 v17, s[0:1], 0, v17, s[0:1]
	global_load_dword v150, v[18:19], off
	global_load_dword v152, v[20:21], off
	global_load_dword v154, v[16:17], off
	v_lshl_add_u64 v[16:17], v[6:7], 0, s[6:7]
	v_add_co_u32_e64 v18, s[0:1], s3, v16
	global_load_dword v156, v[16:17], off
	s_nop 0
	v_addc_co_u32_e64 v19, s[0:1], 0, v17, s[0:1]
	v_add_co_u32_e64 v20, s[0:1], s8, v16
	s_add_u32 s6, s6, 0x18000
	s_nop 0
	v_addc_co_u32_e64 v21, s[0:1], 0, v17, s[0:1]
	v_add_co_u32_e64 v16, s[0:1], s9, v16
	s_addc_u32 s7, s7, 0
	s_nop 0
	v_addc_co_u32_e64 v17, s[0:1], 0, v17, s[0:1]
	global_load_dword v158, v[18:19], off
	global_load_dword v160, v[20:21], off
	global_load_dword v180, v[16:17], off
	v_lshl_add_u64 v[16:17], v[6:7], 0, s[6:7]
	v_add_co_u32_e64 v18, s[0:1], s3, v16
	global_load_dword v182, v[16:17], off
	s_nop 0
	v_addc_co_u32_e64 v19, s[0:1], 0, v17, s[0:1]
	v_add_co_u32_e64 v20, s[0:1], s8, v16
	s_add_u32 s6, s6, 0x18000
	s_nop 0
	v_addc_co_u32_e64 v21, s[0:1], 0, v17, s[0:1]
	v_add_co_u32_e64 v16, s[0:1], s9, v16
	s_addc_u32 s7, s7, 0
	s_nop 0
	v_addc_co_u32_e64 v17, s[0:1], 0, v17, s[0:1]
	global_load_dword v184, v[18:19], off
	global_load_dword v186, v[20:21], off
	global_load_dword v194, v[16:17], off
	v_lshl_add_u64 v[16:17], v[6:7], 0, s[6:7]
	v_add_co_u32_e64 v18, s[0:1], s3, v16
	global_load_dword v196, v[16:17], off
	s_nop 0
	v_addc_co_u32_e64 v19, s[0:1], 0, v17, s[0:1]
	v_add_co_u32_e64 v20, s[0:1], s8, v16
	s_add_u32 s6, s6, 0x18000
	s_nop 0
	v_addc_co_u32_e64 v21, s[0:1], 0, v17, s[0:1]
	v_add_co_u32_e64 v16, s[0:1], s9, v16
	s_addc_u32 s7, s7, 0
	s_nop 0
	v_addc_co_u32_e64 v17, s[0:1], 0, v17, s[0:1]
	global_load_dword v198, v[18:19], off
	global_load_dword v200, v[20:21], off
	global_load_dword v202, v[16:17], off
	v_lshl_add_u64 v[16:17], v[6:7], 0, s[6:7]
	v_add_co_u32_e64 v18, s[0:1], s3, v16
	global_load_dword v204, v[16:17], off
	s_nop 0
	v_addc_co_u32_e64 v19, s[0:1], 0, v17, s[0:1]
	v_add_co_u32_e64 v20, s[0:1], s8, v16
	s_add_u32 s6, s6, 0x18000
	s_nop 0
	v_addc_co_u32_e64 v21, s[0:1], 0, v17, s[0:1]
	v_add_co_u32_e64 v16, s[0:1], s9, v16
	s_addc_u32 s7, s7, 0
	s_nop 0
	v_addc_co_u32_e64 v17, s[0:1], 0, v17, s[0:1]
	global_load_dword v206, v[18:19], off
	global_load_dword v208, v[20:21], off
	global_load_dword v210, v[16:17], off
	v_lshl_add_u64 v[16:17], v[6:7], 0, s[6:7]
	v_add_co_u32_e64 v18, s[0:1], s3, v16
	global_load_dword v212, v[16:17], off
	s_nop 0
	v_addc_co_u32_e64 v19, s[0:1], 0, v17, s[0:1]
	v_add_co_u32_e64 v20, s[0:1], s8, v16
	s_add_u32 s6, s6, 0x18000
	s_nop 0
	v_addc_co_u32_e64 v21, s[0:1], 0, v17, s[0:1]
	v_add_co_u32_e64 v16, s[0:1], s9, v16
	s_addc_u32 s7, s7, 0
	s_nop 0
	v_addc_co_u32_e64 v17, s[0:1], 0, v17, s[0:1]
	global_load_dword v216, v[18:19], off
	global_load_dword v218, v[20:21], off
	global_load_dword v220, v[16:17], off
	ds_read_b128 v[16:19], v15
	ds_read_b128 v[20:23], v15 offset:4096
	ds_read_b128 v[24:27], v15 offset:8192
	ds_read_b128 v[28:31], v15 offset:12288
	ds_read_b128 v[32:35], v15 offset:16384
	s_waitcnt lgkmcnt(4)
	v_mov_b32_e32 v44, v16
	s_waitcnt lgkmcnt(3)
	v_mov_b32_e32 v45, v20
	s_waitcnt lgkmcnt(2)
	v_mov_b32_e32 v46, v24
	s_waitcnt lgkmcnt(1)
	v_mov_b32_e32 v47, v28
	v_mov_b32_e32 v20, v17
	v_mov_b32_e32 v28, v25
	v_mov_b32_e32 v16, v18
	v_mov_b32_e32 v17, v22
	v_mov_b32_e32 v24, v26
	v_mov_b32_e32 v25, v30
	v_mov_b32_e32 v22, v19
	v_mov_b32_e32 v30, v27
	v_add_u32_e32 v15, 16, v15
	s_cmp_eq_u32 s6, 0x300000
	s_waitcnt vmcnt(31)
	v_pk_fma_f32 v[8:9], v[130:131], v[44:45], v[8:9] op_sel_hi:[0,1,1]
	v_pk_fma_f32 v[10:11], v[130:131], v[46:47], v[10:11] op_sel_hi:[0,1,1]
	s_waitcnt lgkmcnt(0)
	v_fmac_f32_e32 v14, v130, v32
	s_waitcnt vmcnt(30)
	v_pk_fma_f32 v[8:9], v[132:133], v[20:21], v[8:9] op_sel_hi:[0,1,1]
	v_pk_fma_f32 v[10:11], v[132:133], v[28:29], v[10:11] op_sel_hi:[0,1,1]
	v_fmac_f32_e32 v14, v132, v33
	s_waitcnt vmcnt(29)
	v_pk_fma_f32 v[8:9], v[134:135], v[16:17], v[8:9] op_sel_hi:[0,1,1]
	v_pk_fma_f32 v[10:11], v[134:135], v[24:25], v[10:11] op_sel_hi:[0,1,1]
	v_fmac_f32_e32 v14, v134, v34
	s_waitcnt vmcnt(28)
; DI void mod_phase(const P& p, float* sm) {
;     ...
;     for (int d = ds * 128; d < ds * 128 + 128; ++d) {
;       float wv = w[(size_t)d * 6144];
; #pragma unroll
;       for (int r = 0; r < 5; ++r) acc[r] += sl[r * 1024 + d] * wv;
;     }
	v_pk_fma_f32 v[8:9], v[136:137], v[22:23], v[8:9] op_sel_hi:[0,1,1]
	v_pk_fma_f32 v[10:11], v[136:137], v[30:31], v[10:11] op_sel_hi:[0,1,1]
	v_fmac_f32_e32 v14, v136, v35
	ds_read_b128 v[16:19], v15
	ds_read_b128 v[20:23], v15 offset:4096
	ds_read_b128 v[24:27], v15 offset:8192
	ds_read_b128 v[28:31], v15 offset:12288
	ds_read_b128 v[32:35], v15 offset:16384
	s_waitcnt lgkmcnt(4)
	v_mov_b32_e32 v44, v16
	s_waitcnt lgkmcnt(3)
	v_mov_b32_e32 v45, v20
	s_waitcnt lgkmcnt(2)
	v_mov_b32_e32 v46, v24
	s_waitcnt lgkmcnt(1)
	v_mov_b32_e32 v47, v28
	v_mov_b32_e32 v20, v17
	v_mov_b32_e32 v28, v25
	v_mov_b32_e32 v16, v18
	v_mov_b32_e32 v17, v22
	v_mov_b32_e32 v24, v26
	v_mov_b32_e32 v25, v30
	v_mov_b32_e32 v22, v19
	v_mov_b32_e32 v30, v27
	v_add_u32_e32 v15, 16, v15
	s_cmp_eq_u32 s6, 0x300000
	s_waitcnt vmcnt(27)
	v_pk_fma_f32 v[8:9], v[138:139], v[44:45], v[8:9] op_sel_hi:[0,1,1]
	v_pk_fma_f32 v[10:11], v[138:139], v[46:47], v[10:11] op_sel_hi:[0,1,1]
	s_waitcnt lgkmcnt(0)
	v_fmac_f32_e32 v14, v138, v32
	s_waitcnt vmcnt(26)
	v_pk_fma_f32 v[8:9], v[140:141], v[20:21], v[8:9] op_sel_hi:[0,1,1]
	v_pk_fma_f32 v[10:11], v[140:141], v[28:29], v[10:11] op_sel_hi:[0,1,1]
	v_fmac_f32_e32 v14, v140, v33
	s_waitcnt vmcnt(25)
	v_pk_fma_f32 v[8:9], v[142:143], v[16:17], v[8:9] op_sel_hi:[0,1,1]
	v_pk_fma_f32 v[10:11], v[142:143], v[24:25], v[10:11] op_sel_hi:[0,1,1]
	v_fmac_f32_e32 v14, v142, v34
	s_waitcnt vmcnt(24)
	v_pk_fma_f32 v[8:9], v[144:145], v[22:23], v[8:9] op_sel_hi:[0,1,1]
	v_pk_fma_f32 v[10:11], v[144:145], v[30:31], v[10:11] op_sel_hi:[0,1,1]
	v_fmac_f32_e32 v14, v144, v35
	ds_read_b128 v[16:19], v15
	ds_read_b128 v[20:23], v15 offset:4096
	ds_read_b128 v[24:27], v15 offset:8192
	ds_read_b128 v[28:31], v15 offset:12288
	ds_read_b128 v[32:35], v15 offset:16384
	s_waitcnt lgkmcnt(4)
	v_mov_b32_e32 v44, v16
	s_waitcnt lgkmcnt(3)
	v_mov_b32_e32 v45, v20
	s_waitcnt lgkmcnt(2)
	v_mov_b32_e32 v46, v24
	s_waitcnt lgkmcnt(1)
	v_mov_b32_e32 v47, v28
	v_mov_b32_e32 v20, v17
	v_mov_b32_e32 v28, v25
	v_mov_b32_e32 v16, v18
	v_mov_b32_e32 v17, v22
	v_mov_b32_e32 v24, v26
	v_mov_b32_e32 v25, v30
	v_mov_b32_e32 v22, v19
	v_mov_b32_e32 v30, v27
	v_add_u32_e32 v15, 16, v15
	s_cmp_eq_u32 s6, 0x300000
	s_waitcnt vmcnt(23)
	v_pk_fma_f32 v[8:9], v[146:147], v[44:45], v[8:9] op_sel_hi:[0,1,1]
	v_pk_fma_f32 v[10:11], v[146:147], v[46:47], v[10:11] op_sel_hi:[0,1,1]
	s_waitcnt lgkmcnt(0)
	v_fmac_f32_e32 v14, v146, v32
	s_waitcnt vmcnt(22)
	v_pk_fma_f32 v[8:9], v[150:151], v[20:21], v[8:9] op_sel_hi:[0,1,1]
	v_pk_fma_f32 v[10:11], v[150:151], v[28:29], v[10:11] op_sel_hi:[0,1,1]
	v_fmac_f32_e32 v14, v150, v33
	s_waitcnt vmcnt(21)
	v_pk_fma_f32 v[8:9], v[152:153], v[16:17], v[8:9] op_sel_hi:[0,1,1]
	v_pk_fma_f32 v[10:11], v[152:153], v[24:25], v[10:11] op_sel_hi:[0,1,1]
	v_fmac_f32_e32 v14, v152, v34
	s_waitcnt vmcnt(20)
	v_pk_fma_f32 v[8:9], v[154:155], v[22:23], v[8:9] op_sel_hi:[0,1,1]
	v_pk_fma_f32 v[10:11], v[154:155], v[30:31], v[10:11] op_sel_hi:[0,1,1]
	v_fmac_f32_e32 v14, v154, v35
	ds_read_b128 v[16:19], v15
	ds_read_b128 v[20:23], v15 offset:4096
	ds_read_b128 v[24:27], v15 offset:8192
	ds_read_b128 v[28:31], v15 offset:12288
	ds_read_b128 v[32:35], v15 offset:16384
	s_waitcnt lgkmcnt(4)
	v_mov_b32_e32 v44, v16
	s_waitcnt lgkmcnt(3)
	v_mov_b32_e32 v45, v20
	s_waitcnt lgkmcnt(2)
	v_mov_b32_e32 v46, v24
	s_waitcnt lgkmcnt(1)
	v_mov_b32_e32 v47, v28
	v_mov_b32_e32 v20, v17
	v_mov_b32_e32 v28, v25
	v_mov_b32_e32 v16, v18
	v_mov_b32_e32 v17, v22
	v_mov_b32_e32 v24, v26
	v_mov_b32_e32 v25, v30
	v_mov_b32_e32 v22, v19
	v_mov_b32_e32 v30, v27
	v_add_u32_e32 v15, 16, v15
	s_cmp_eq_u32 s6, 0x300000
	s_waitcnt vmcnt(19)
	v_pk_fma_f32 v[8:9], v[156:157], v[44:45], v[8:9] op_sel_hi:[0,1,1]
	v_pk_fma_f32 v[10:11], v[156:157], v[46:47], v[10:11] op_sel_hi:[0,1,1]
	s_waitcnt lgkmcnt(0)
	v_fmac_f32_e32 v14, v156, v32
	s_waitcnt vmcnt(18)
	v_pk_fma_f32 v[8:9], v[158:159], v[20:21], v[8:9] op_sel_hi:[0,1,1]
	v_pk_fma_f32 v[10:11], v[158:159], v[28:29], v[10:11] op_sel_hi:[0,1,1]
	v_fmac_f32_e32 v14, v158, v33
	s_waitcnt vmcnt(17)
	v_pk_fma_f32 v[8:9], v[160:161], v[16:17], v[8:9] op_sel_hi:[0,1,1]
	v_pk_fma_f32 v[10:11], v[160:161], v[24:25], v[10:11] op_sel_hi:[0,1,1]
	v_fmac_f32_e32 v14, v160, v34
	s_waitcnt vmcnt(16)
	v_pk_fma_f32 v[8:9], v[180:181], v[22:23], v[8:9] op_sel_hi:[0,1,1]
	v_pk_fma_f32 v[10:11], v[180:181], v[30:31], v[10:11] op_sel_hi:[0,1,1]
	v_fmac_f32_e32 v14, v180, v35
	ds_read_b128 v[16:19], v15
	ds_read_b128 v[20:23], v15 offset:4096
	ds_read_b128 v[24:27], v15 offset:8192
	ds_read_b128 v[28:31], v15 offset:12288
	ds_read_b128 v[32:35], v15 offset:16384
	s_waitcnt lgkmcnt(4)
	v_mov_b32_e32 v44, v16
	s_waitcnt lgkmcnt(3)
	v_mov_b32_e32 v45, v20
	s_waitcnt lgkmcnt(2)
	v_mov_b32_e32 v46, v24
	s_waitcnt lgkmcnt(1)
	v_mov_b32_e32 v47, v28
	v_mov_b32_e32 v20, v17
	v_mov_b32_e32 v28, v25
	v_mov_b32_e32 v16, v18
	v_mov_b32_e32 v17, v22
	v_mov_b32_e32 v24, v26
	v_mov_b32_e32 v25, v30
	v_mov_b32_e32 v22, v19
	v_mov_b32_e32 v30, v27
	v_add_u32_e32 v15, 16, v15
	s_cmp_eq_u32 s6, 0x300000
	s_waitcnt vmcnt(15)
	v_pk_fma_f32 v[8:9], v[182:183], v[44:45], v[8:9] op_sel_hi:[0,1,1]
	v_pk_fma_f32 v[10:11], v[182:183], v[46:47], v[10:11] op_sel_hi:[0,1,1]
	s_waitcnt lgkmcnt(0)
	v_fmac_f32_e32 v14, v182, v32
	s_waitcnt vmcnt(14)
	v_pk_fma_f32 v[8:9], v[184:185], v[20:21], v[8:9] op_sel_hi:[0,1,1]
	v_pk_fma_f32 v[10:11], v[184:185], v[28:29], v[10:11] op_sel_hi:[0,1,1]
	v_fmac_f32_e32 v14, v184, v33
	s_waitcnt vmcnt(13)
	v_pk_fma_f32 v[8:9], v[186:187], v[16:17], v[8:9] op_sel_hi:[0,1,1]
	v_pk_fma_f32 v[10:11], v[186:187], v[24:25], v[10:11] op_sel_hi:[0,1,1]
	v_fmac_f32_e32 v14, v186, v34
	s_waitcnt vmcnt(12)
; DI void mod_phase(const P& p, float* sm) {
;     ...
;     for (int d = ds * 128; d < ds * 128 + 128; ++d) {
;       float wv = w[(size_t)d * 6144];
; #pragma unroll
;       for (int r = 0; r < 5; ++r) acc[r] += sl[r * 1024 + d] * wv;
;     }
;     __syncthreads();
; #pragma unroll
;     for (int r = 0; r < 5; ++r) red[(ds * 5 + r) * 64 + col] = acc[r];
;     __syncthreads();
;     if (tid < 320) {
;       int r = tid >> 6, cc = tid & 63;
;       float s = 0.f;
;       for (int k = 0; k < 8; ++k) s += red[(k * 5 + r) * 64 + cc];
;       MOD[(l * 5 + r) * 6144 + c0 + cc] = s + p.in[I_BMOD][l * 6144 + c0 + cc];
;     }
	v_pk_fma_f32 v[8:9], v[194:195], v[22:23], v[8:9] op_sel_hi:[0,1,1]
	v_pk_fma_f32 v[10:11], v[194:195], v[30:31], v[10:11] op_sel_hi:[0,1,1]
	v_fmac_f32_e32 v14, v194, v35
	ds_read_b128 v[16:19], v15
	ds_read_b128 v[20:23], v15 offset:4096
	ds_read_b128 v[24:27], v15 offset:8192
	ds_read_b128 v[28:31], v15 offset:12288
	ds_read_b128 v[32:35], v15 offset:16384
	s_waitcnt lgkmcnt(4)
	v_mov_b32_e32 v44, v16
	s_waitcnt lgkmcnt(3)
	v_mov_b32_e32 v45, v20
	s_waitcnt lgkmcnt(2)
	v_mov_b32_e32 v46, v24
	s_waitcnt lgkmcnt(1)
	v_mov_b32_e32 v47, v28
	v_mov_b32_e32 v20, v17
	v_mov_b32_e32 v28, v25
	v_mov_b32_e32 v16, v18
	v_mov_b32_e32 v17, v22
	v_mov_b32_e32 v24, v26
	v_mov_b32_e32 v25, v30
	v_mov_b32_e32 v22, v19
	v_mov_b32_e32 v30, v27
	v_add_u32_e32 v15, 16, v15
	s_cmp_eq_u32 s6, 0x300000
	s_waitcnt vmcnt(11)
	v_pk_fma_f32 v[8:9], v[196:197], v[44:45], v[8:9] op_sel_hi:[0,1,1]
	v_pk_fma_f32 v[10:11], v[196:197], v[46:47], v[10:11] op_sel_hi:[0,1,1]
	s_waitcnt lgkmcnt(0)
	v_fmac_f32_e32 v14, v196, v32
	s_waitcnt vmcnt(10)
	v_pk_fma_f32 v[8:9], v[198:199], v[20:21], v[8:9] op_sel_hi:[0,1,1]
	v_pk_fma_f32 v[10:11], v[198:199], v[28:29], v[10:11] op_sel_hi:[0,1,1]
	v_fmac_f32_e32 v14, v198, v33
	s_waitcnt vmcnt(9)
	v_pk_fma_f32 v[8:9], v[200:201], v[16:17], v[8:9] op_sel_hi:[0,1,1]
	v_pk_fma_f32 v[10:11], v[200:201], v[24:25], v[10:11] op_sel_hi:[0,1,1]
	v_fmac_f32_e32 v14, v200, v34
	s_waitcnt vmcnt(8)
	v_pk_fma_f32 v[8:9], v[202:203], v[22:23], v[8:9] op_sel_hi:[0,1,1]
	v_pk_fma_f32 v[10:11], v[202:203], v[30:31], v[10:11] op_sel_hi:[0,1,1]
	v_fmac_f32_e32 v14, v202, v35
	ds_read_b128 v[16:19], v15
	ds_read_b128 v[20:23], v15 offset:4096
	ds_read_b128 v[24:27], v15 offset:8192
	ds_read_b128 v[28:31], v15 offset:12288
	ds_read_b128 v[32:35], v15 offset:16384
	s_waitcnt lgkmcnt(4)
	v_mov_b32_e32 v44, v16
	s_waitcnt lgkmcnt(3)
	v_mov_b32_e32 v45, v20
	s_waitcnt lgkmcnt(2)
	v_mov_b32_e32 v46, v24
	s_waitcnt lgkmcnt(1)
	v_mov_b32_e32 v47, v28
	v_mov_b32_e32 v20, v17
	v_mov_b32_e32 v28, v25
	v_mov_b32_e32 v16, v18
	v_mov_b32_e32 v17, v22
	v_mov_b32_e32 v24, v26
	v_mov_b32_e32 v25, v30
	v_mov_b32_e32 v22, v19
	v_mov_b32_e32 v30, v27
	v_add_u32_e32 v15, 16, v15
	s_cmp_eq_u32 s6, 0x300000
	s_waitcnt vmcnt(7)
	v_pk_fma_f32 v[8:9], v[204:205], v[44:45], v[8:9] op_sel_hi:[0,1,1]
	v_pk_fma_f32 v[10:11], v[204:205], v[46:47], v[10:11] op_sel_hi:[0,1,1]
	s_waitcnt lgkmcnt(0)
	v_fmac_f32_e32 v14, v204, v32
	s_waitcnt vmcnt(6)
	v_pk_fma_f32 v[8:9], v[206:207], v[20:21], v[8:9] op_sel_hi:[0,1,1]
	v_pk_fma_f32 v[10:11], v[206:207], v[28:29], v[10:11] op_sel_hi:[0,1,1]
	v_fmac_f32_e32 v14, v206, v33
	s_waitcnt vmcnt(5)
	v_pk_fma_f32 v[8:9], v[208:209], v[16:17], v[8:9] op_sel_hi:[0,1,1]
	v_pk_fma_f32 v[10:11], v[208:209], v[24:25], v[10:11] op_sel_hi:[0,1,1]
	v_fmac_f32_e32 v14, v208, v34
	s_waitcnt vmcnt(4)
	v_pk_fma_f32 v[8:9], v[210:211], v[22:23], v[8:9] op_sel_hi:[0,1,1]
	v_pk_fma_f32 v[10:11], v[210:211], v[30:31], v[10:11] op_sel_hi:[0,1,1]
	v_fmac_f32_e32 v14, v210, v35
	ds_read_b128 v[16:19], v15
	ds_read_b128 v[20:23], v15 offset:4096
	ds_read_b128 v[24:27], v15 offset:8192
	ds_read_b128 v[28:31], v15 offset:12288
	ds_read_b128 v[32:35], v15 offset:16384
	s_waitcnt lgkmcnt(4)
	v_mov_b32_e32 v44, v16
	s_waitcnt lgkmcnt(3)
	v_mov_b32_e32 v45, v20
	s_waitcnt lgkmcnt(2)
	v_mov_b32_e32 v46, v24
	s_waitcnt lgkmcnt(1)
	v_mov_b32_e32 v47, v28
	v_mov_b32_e32 v20, v17
	v_mov_b32_e32 v28, v25
	v_mov_b32_e32 v16, v18
	v_mov_b32_e32 v17, v22
	v_mov_b32_e32 v24, v26
	v_mov_b32_e32 v25, v30
	v_mov_b32_e32 v22, v19
	v_mov_b32_e32 v30, v27
	v_add_u32_e32 v15, 16, v15
	s_cmp_eq_u32 s6, 0x300000
	s_waitcnt vmcnt(3)
	v_pk_fma_f32 v[8:9], v[212:213], v[44:45], v[8:9] op_sel_hi:[0,1,1]
	v_pk_fma_f32 v[10:11], v[212:213], v[46:47], v[10:11] op_sel_hi:[0,1,1]
	s_waitcnt lgkmcnt(0)
	v_fmac_f32_e32 v14, v212, v32
	s_waitcnt vmcnt(2)
	v_pk_fma_f32 v[8:9], v[216:217], v[20:21], v[8:9] op_sel_hi:[0,1,1]
	v_pk_fma_f32 v[10:11], v[216:217], v[28:29], v[10:11] op_sel_hi:[0,1,1]
	v_fmac_f32_e32 v14, v216, v33
	s_waitcnt vmcnt(1)
	v_pk_fma_f32 v[8:9], v[218:219], v[16:17], v[8:9] op_sel_hi:[0,1,1]
	v_pk_fma_f32 v[10:11], v[218:219], v[24:25], v[10:11] op_sel_hi:[0,1,1]
	v_fmac_f32_e32 v14, v218, v34
	s_waitcnt vmcnt(0)
	v_pk_fma_f32 v[8:9], v[220:221], v[22:23], v[8:9] op_sel_hi:[0,1,1]
	v_pk_fma_f32 v[10:11], v[220:221], v[30:31], v[10:11] op_sel_hi:[0,1,1]
	v_fmac_f32_e32 v14, v220, v35
	s_cbranch_scc0 .LBB0_55
	s_barrier
	ds_write2st64_b32 v12, v8, v9 offset0:80 offset1:81
	ds_write2st64_b32 v12, v10, v11 offset0:82 offset1:83
	ds_write_b32 v12, v14 offset:21504
	s_waitcnt lgkmcnt(0)
	s_barrier
	s_and_saveexec_b64 s[0:1], vcc
	s_cbranch_execz .LBB0_53
	s_mul_i32 s5, s14, 0x1800
	s_add_i32 s5, s5, s4
	v_or_b32_e32 v6, s5, v1
	v_ashrrev_i32_e32 v7, 31, v6
	v_lshl_add_u64 v[6:7], v[6:7], 2, s[78:79]
	global_load_dword v18, v[6:7], off
	ds_read2st64_b32 v[6:7], v13 offset0:80 offset1:85
	ds_read2st64_b32 v[8:9], v13 offset0:90 offset1:95
	ds_read2st64_b32 v[10:11], v13 offset0:100 offset1:105
	ds_read2st64_b32 v[14:15], v13 offset0:110 offset1:115
	v_mad_u64_u32 v[16:17], s[6:7], s14, 5, v[2:3]
	s_waitcnt lgkmcnt(3)
	v_add_f32_e32 v6, 0, v6
	v_add_f32_e32 v6, v6, v7
	s_waitcnt lgkmcnt(2)
	v_add_f32_e32 v6, v6, v8
	v_add_f32_e32 v6, v6, v9
	v_mul_lo_u32 v16, v16, s12
	s_waitcnt lgkmcnt(1)
	v_add_f32_e32 v6, v6, v10
	v_add_u32_e32 v16, s4, v16
	v_add_f32_e32 v6, v6, v11
	v_or_b32_e32 v16, v16, v1
	s_waitcnt lgkmcnt(0)
	v_add_f32_e32 v6, v6, v14
	v_ashrrev_i32_e32 v17, 31, v16
	v_add_f32_e32 v6, v6, v15
	s_waitcnt vmcnt(0)
	v_add_f32_e32 v8, v6, v18
	v_lshl_add_u64 v[6:7], v[16:17], 2, s[60:61]
	global_store_dword v[6:7], v8, off
	s_branch .LBB0_53
